# P3 units and scan (b,h) remapped class-aligned; P3-P4 seam becomes a class barrier, scan workgroups additionally wait on a device-wide P3-done counter before writing o over PA
# baseline (speedup 1.0000x reference)
.LBB0_182:
	s_or_b64 exec, exec, s[6:7]
	v_mov_b32_e32 v35, v211
	s_and_b32 s4, s74, 7
	s_lshl_b32 s4, s4, 5
	s_lshr_b32 s80, s74, 3
	s_or_b32 s4, s4, s80
	s_mov_b32 s80, s94
	s_mov_b32 s82, s75
	s_waitcnt lgkmcnt(0)
	s_barrier
	v_readlane_b32 s1, v255, 31
	v_readfirstlane_b32 s0, v35
	s_mov_b64 s[8:9], s[92:93]
	s_cmpk_lt_i32 s4, 0x100
	s_cbranch_scc0 .LBB0_318
	s_mul_i32 s2, s1, 0x1800
	s_ashr_i32 s3, s2, 31
	v_readlane_b32 s12, v254, 10
	s_lshl_b64 s[2:3], s[2:3], 2
	v_readlane_b32 s14, v254, 12
	v_readlane_b32 s20, v254, 18
	v_readlane_b32 s15, v254, 13
	v_readlane_b32 s21, v254, 19
	s_add_u32 s14, s20, s2
	v_readlane_b32 s16, v254, 14
	s_addc_u32 s15, s21, s3
	s_ashr_i32 s12, s0, 6
	v_readlane_b32 s17, v254, 15
	s_add_u32 s16, s8, 0x140000
	v_readlane_b32 s18, v254, 16
	s_addc_u32 s17, s9, 0
	v_readlane_b32 s19, v254, 17
	v_and_b32_e32 v34, 3, v35
	s_add_u32 s18, s8, 0x180000
	s_movk_i32 s1, 0x100
	v_ashrrev_i32_e32 v32, 2, v35
	v_lshlrev_b32_e32 v1, 6, v34
	s_addc_u32 s19, s9, 0
	v_cmp_gt_i32_e64 s[38:39], s1, v35
	v_add_lshl_u32 v1, v1, v32, 2
	v_readlane_b32 s1, v255, 25
	s_cmp_lt_i32 s12, 4
	s_cselect_b64 s[60:61], -1, 0
	v_add_u32_e32 v39, s1, v1
	s_and_b32 s1, s0, 0xffffffc0
	s_add_u32 s81, s8, 0x9e00000
	v_readlane_b32 s3, v255, 24
	s_addc_u32 s75, s9, 0
	v_readlane_b32 s13, v254, 11
	v_add_u32_e32 v38, s3, v1
	v_mov_b32_e32 v1, s0
	s_movk_i32 s2, 0xffc0
	s_add_u32 s62, s8, 0x3e00000
	v_bfi_b32 v1, s2, v1, v35
	s_addc_u32 s63, s9, 0
	s_and_b32 s13, s12, 1
	v_lshlrev_b32_e32 v1, 2, v1
	s_bitcmp1_b32 s0, 7
	v_add_u32_e32 v40, s3, v1
	s_cselect_b64 s[2:3], -1, 0
	s_cmp_eq_u32 s13, 0
	s_cselect_b64 s[6:7], -1, 0
	s_or_b64 s[64:65], s[2:3], s[6:7]
	s_cmpk_gt_u32 s0, 0xff
	s_cselect_b64 s[66:67], -1, 0
	s_lshr_b32 s2, s0, 2
	s_and_b32 s2, s2, 32
	s_lshl_b32 s36, s13, 5
	s_cmp_gt_i32 s12, 1
	s_mul_i32 s3, s12, 0x2200
	v_readlane_b32 s22, v254, 20
	s_cselect_b64 s[68:69], -1, 0
	s_lshl_b32 s6, s12, 7
	s_add_i32 s3, s3, 0
	s_add_i32 s21, s3, s6
	s_add_i32 s22, s1, 0
	s_lshl_b32 s37, s12, 5
	s_add_i32 s20, s21, 0x16000
	s_add_i32 s21, s21, 0x1d400
	s_add_i32 s22, s22, 0x1a400
	s_cmp_lt_u32 s0, 64
	s_cselect_b64 s[70:71], -1, 0
	s_cmpk_lt_u32 s0, 0x100
	s_cselect_b64 s[72:73], -1, 0
	s_and_b64 s[0:1], s[72:73], exec
	v_readlane_b32 s23, v254, 21
	v_readlane_b32 s0, v255, 26
	v_readlane_b32 s24, v254, 22
	v_readlane_b32 s25, v254, 23
	s_cselect_b32 s23, 0, s0
	v_readlane_b32 s0, v255, 27
	s_cselect_b32 s24, s0, s88
	s_and_b32 s25, s37, 0x60
	v_readlane_b32 s26, v254, 24
	s_add_u32 s6, s8, 0xdb00000
	v_readlane_b32 s27, v254, 25
	s_addc_u32 s7, s9, 0
	s_lshl_b32 s26, s12, 1
	v_and_b32_e32 v0, 63, v35
	s_add_u32 s27, s8, 0x100000
	s_mulk_i32 s12, 0x1200
	v_ashrrev_i32_e32 v33, 31, v32
	v_add_u32_e32 v41, s84, v1
	s_addc_u32 s96, s9, 0
	v_cmp_eq_u32_e64 s[40:41], 0, v0
	v_cmp_gt_u32_e64 s[42:43], 2, v0
	v_cmp_gt_u32_e64 s[44:45], 4, v0
	v_cmp_gt_u32_e64 s[46:47], 8, v0
	v_cmp_gt_u32_e64 s[48:49], 16, v0
	v_cmp_gt_u32_e64 s[50:51], 32, v0
	s_xor_b32 s97, s25, 32
	s_xor_b32 s3, s25, 64
	s_xor_b32 s0, s25, 0x60
	s_add_i32 s1, s22, s12
	s_branch .LBB0_185

.LBB0_318:
	s_waitcnt vmcnt(0)
	v_readlane_b32 s76, v255, 33
	v_readlane_b32 s78, v255, 35
	v_readlane_b32 s80, v255, 37
	v_readlane_b32 s77, v255, 34
	v_readlane_b32 s79, v255, 36
	v_readlane_b32 s81, v255, 38
	s_mov_b32 s75, s82
	s_barrier
	s_mov_b64 s[6:7], exec
	v_readlane_b32 s0, v254, 8
	v_readlane_b32 s1, v254, 9
	s_and_b64 s[0:1], s[6:7], s[0:1]
	s_mov_b64 exec, s[0:1]
	s_cbranch_execz .LBB0_370
	v_readlane_b32 s0, v255, 41
	s_cmp_eq_u32 s0, 1
	s_cbranch_scc1 .Llb370_go
	s_cmp_eq_u32 s0, 2
	s_cbranch_scc1 .Llb370_global
	s_add_u32 s2, s92, 0x5000
	s_addc_u32 s3, s93, 0
	s_waitcnt vmcnt(0) lgkmcnt(0)
	global_load_dword v0, v197, s[2:3] offset:128 sc1
	s_waitcnt vmcnt(0)
	v_readfirstlane_b32 s0, v0
	s_cmp_eq_u32 s0, 0
	s_cselect_b32 s0, 1, 2
	s_nop 0
	v_writelane_b32 v255, s0, 41
	s_cmp_eq_u32 s0, 1
	s_cbranch_scc0 .Llb370_global
.Llb370_go:
	s_and_b32 s0, s74, 7
	s_lshl_b32 s0, s0, 8
	s_add_u32 s0, s0, 0x4000
	s_add_u32 s2, s92, s0
	s_addc_u32 s3, s93, 0
	v_mov_b32_e32 v0, 1
	s_waitcnt vmcnt(0) lgkmcnt(0)
	s_add_u32 s12, s92, 0x5140
	s_addc_u32 s13, s93, 0
	global_atomic_add v197, v0, s[12:13]
	s_add_u32 s12, s92, 0x5140
	s_addc_u32 s13, s93, 0
	global_load_dword v2, v197, s[12:13] sc1
	global_atomic_add v1, v197, v0, s[2:3] sc0
	buffer_inv sc1
	s_waitcnt vmcnt(0)
	v_readfirstlane_b32 s1, v1
	s_lshr_b32 s8, s1, 5
	s_and_b32 s1, s1, 31
	s_cmp_eq_u32 s1, 31
	s_cbranch_scc1 .Llb370_lead
	s_mov_b32 s9, 0

.Llb370_fin:
	s_cmp_gt_u32 s74, 31
	s_cbranch_scc1 .LBB0_370
	v_readfirstlane_b32 s1, v2
	v_readlane_b32 s0, v255, 31
	s_add_u32 s0, s0, 1
	s_lshl_b32 s0, s0, 8
	s_mov_b32 s9, 0

.LBB0_370:
	s_or_b64 exec, exec, s[6:7]
	v_mov_b32_e32 v212, v211
	s_waitcnt lgkmcnt(0)
	s_barrier
	s_mov_b32 s1, s94
	v_readfirstlane_b32 s2, v212
	s_ashr_i32 s16, s2, 6
	s_mov_b32 s0, s74
	v_bfe_u32 v199, v212, 5, 1
	v_readlane_b32 s3, v255, 31
	v_and_b32_e32 v231, 63, v212
	v_and_b32_e32 v210, 31, v212
	s_mov_b32 s18, s3
	s_mov_b64 s[14:15], s[92:93]
	s_cmp_gt_i32 s0, 31
	v_lshlrev_b32_e32 v232, 3, v199
	s_cbranch_scc1 .LBB0_514
	s_and_b32 s3, s0, 7
	s_lshl_b32 s3, s3, 2
	s_lshr_b32 s0, s0, 3
	s_or_b32 s0, s0, s3
	s_add_u32 s3, s14, 0x9e00000
	s_addc_u32 s19, s15, 0
	s_cmp_lt_i32 s16, 4
	s_cselect_b64 s[6:7], -1, 0
	s_add_u32 s8, s14, 0x100000
	s_addc_u32 s9, s15, 0
	s_ashr_i32 s17, s16, 31
	s_lshl_b64 s[12:13], s[16:17], 12
	s_add_u32 s12, s14, s12
	s_addc_u32 s13, s15, s13
	v_lshlrev_b32_e32 v196, 4, v231
	v_lshl_add_u64 v[0:1], s[12:13], 0, v[196:197]
	s_mov_b64 s[12:13], 0xdb00000
	v_lshl_add_u64 v[214:215], v[0:1], 0, s[12:13]
	v_lshlrev_b32_e32 v1, 4, v199
	v_lshlrev_b32_e32 v2, 1, v212
	v_bitop3_b32 v196, v1, v212, 16 bitop3:0x78
	v_and_b32_e32 v1, 1, v212
	v_and_b32_e32 v2, 60, v2
	s_movk_i32 s4, 0xf40
	s_add_u32 s17, s14, 0x3e00000
	v_cmp_eq_u32_e64 s[40:41], 0, v1
	v_lshl_or_b32 v1, v1, 10, v2
	v_cmp_gt_i32_e64 s[38:39], s4, v212
	s_addc_u32 s20, s15, 0
	s_and_b32 s4, s2, 0xffffffc0
	v_lshl_or_b32 v1, v199, 12, v1
	v_lshlrev_b32_e32 v233, 4, v212
	v_mul_u32_u24_e32 v0, 0x48, v210
	v_add_u32_e32 v213, s4, v1
	v_lshlrev_b32_e32 v1, 8, v212
	v_and_b32_e32 v2, 0xf0, v233
	s_movk_i32 s4, 0xf000
	v_and_or_b32 v1, v1, s4, v2
	v_lshlrev_b32_e32 v236, 1, v232
	v_lshlrev_b32_e32 v0, 1, v0
	v_readlane_b32 s4, v255, 28
	v_add_u32_e32 v216, 0xffff0000, v1
	v_ashrrev_i32_e32 v217, 31, v216
	v_add3_u32 v239, s4, v0, v236
	s_mov_b32 s4, 0xf400
	v_add_u32_e32 v0, 0xffff0100, v1
	v_cmp_gt_i32_e64 s[44:45], s4, v0
	v_add_u32_e32 v0, 0xffff0200, v1
	v_cmp_gt_i32_e64 s[46:47], s4, v0
	v_add_u32_e32 v0, 0xffff0300, v1
	v_cmp_gt_i32_e64 s[48:49], s4, v0
	v_add_u32_e32 v0, 0xffff0400, v1
	v_cmp_gt_i32_e64 s[50:51], s4, v0
	v_add_u32_e32 v0, 0xffff0500, v1
	v_cmp_gt_i32_e64 s[52:53], s4, v0
	v_add_u32_e32 v0, 0xffff0600, v1
	v_cmp_gt_i32_e64 s[54:55], s4, v0
	v_add_u32_e32 v0, 0xffff0700, v1
	v_cmp_gt_i32_e64 s[56:57], s4, v0
	v_add_u32_e32 v0, 0xffff0800, v1
	v_cmp_gt_i32_e64 s[58:59], s4, v0
	v_add_u32_e32 v0, 0xffff0900, v1
	v_cmp_gt_i32_e64 s[60:61], s4, v0
	v_add_u32_e32 v0, 0xffff0a00, v1
	v_cmp_gt_i32_e64 s[62:63], s4, v0
	v_add_u32_e32 v0, 0xffff0b00, v1
	v_cmp_gt_i32_e64 s[64:65], s4, v0
	v_add_u32_e32 v0, 0xffff0c00, v1
	v_cmp_gt_i32_e64 s[66:67], s4, v0
	v_add_u32_e32 v0, 0xffff0d00, v1
	v_cmp_gt_i32_e64 s[68:69], s4, v0
	v_add_u32_e32 v0, 0xffff0e00, v1
	v_cmp_gt_i32_e64 s[70:71], s4, v0
	v_add_u32_e32 v0, 0xffff0f00, v1
	v_mad_u32_u24 v235, v210, s87, 0
	v_cmp_gt_i32_e64 s[72:73], s4, v0
	v_lshlrev_b32_e32 v0, 7, v210
	v_add_u32_e32 v234, 0, v216
	v_add_u32_e32 v237, v235, v236
	v_sub_u32_e32 v244, 0, v0
	s_lshl_b32 s21, s0, 5
	v_lshl_add_u64 v[0:1], s[14:15], 0, v[216:217]
	s_mov_b64 s[12:13], 0x9e3df00
	v_add_u32_e32 v238, 0xf400, v237
	v_cmp_gt_i32_e64 s[42:43], s4, v216
	v_add_u32_e32 v240, 0x10000, v234
	v_add_u32_e32 v241, 0x10100, v234
	v_add_u32_e32 v242, 0x10200, v234
	v_add_u32_e32 v243, 0x10300, v234
	v_add_u32_e32 v245, 0xfffffe00, v212
	s_or_b32 s22, s21, 1
	s_lshl_b32 s23, s1, 5
	s_lshl_b32 s24, s0, 7
	s_lshl_b32 s25, s1, 7
	v_lshl_add_u64 v[218:219], v[0:1], 0, s[12:13]
	s_mov_b32 s26, s0
	s_branch .LBB0_374
